# GLA scan rewritten: 128 WGs x 2 value slices, every wave owns one 32x32 state tile, o from LDS-published bf16 state with 16x16x32 MFMA, 3-step register prefetch, one barrier per step
# speedup vs baseline: 1.0135x; 1.0066x over previous
.LBB0_153:
	s_andn2_b64 vcc, exec, s[0:1]
	s_cbranch_vccnz .LBB0_176
	s_cmpk_gt_i32 s2, 0x7f
	s_cbranch_scc1 .LBB0_176
	s_and_b32 s0, s2, 7
	s_lshr_b32 s1, s2, 3
	s_and_b32 s5, s1, 3
	s_lshl_b32 s0, s0, 2
	s_add_i32 s0, s0, s5
	s_lshr_b32 s1, s1, 2
	v_lshrrev_b32_e32 v64, 6, v220
	s_nop 0
	v_readfirstlane_b32 s5, v64
	s_nop 0
	s_and_b32 s7, s5, 3
	s_lshr_b32 s9, s5, 2
	s_lshl_b32 s14, s0, 20
	s_add_u32 s24, s92, s14
	s_addc_u32 s25, s93, 0
	s_add_u32 s46, s24, 0x2000
	s_addc_u32 s47, s25, 0
	s_add_u32 s28, s24, 0x2000000
	s_addc_u32 s29, s25, 0
	s_add_u32 s48, s28, 0x2000
	s_addc_u32 s49, s29, 0
	s_lshl_b32 s14, s0, 15
	s_add_u32 s14, s14, 0x1fdc4000
	s_add_u32 s38, s20, s14
	s_addc_u32 s39, s21, 0
	s_lshl_b32 s14, s0, 21
	s_add_u32 s15, s14, 0x1cdc4000
	s_sub_u32 s14, s14, 0x3000000
	s_add_u32 s14, s14, 0x29c4000
	s_cmp_lt_u32 s0, 24
	s_cselect_b32 s14, s15, s14
	s_lshl_b32 s15, s1, 13
	s_add_u32 s14, s14, s15
	s_add_u32 s40, s20, s14
	s_addc_u32 s41, s21, 0
	s_lshr_b32 s14, s0, 2
	s_mul_i32 s14, s14, 0x1a00000
	s_add_u32 s42, s96, s14
	s_addc_u32 s43, s97, 0
	v_lshlrev_b32_e32 v164, 4, v220
	v_and_b32_e32 v64, 31, v220
	v_lshlrev_b32_e32 v208, 4, v64
	v_add_u32_e32 v92, 35840, v208
	s_movk_i32 s14, 0x110
	s_movk_i32 s15, 0x90
	s_movk_i32 s45, 0x1a00
	v_lshrrev_b32_e32 v64, 4, v220
	v_and_b32_e32 v65, 15, v220
	v_lshlrev_b32_e32 v65, 4, v65
	v_mad_u32_u24 v209, v64, s14, v65
	v_lshrrev_b32_e32 v64, 3, v220
	v_and_b32_e32 v65, 7, v220
	v_lshlrev_b32_e32 v65, 4, v65
	v_mad_u32_u24 v210, v64, s15, v65
	v_add_u32_e32 v210, 17408, v210
	v_and_b32_e32 v64, 15, v227
	v_lshrrev_b32_e32 v65, 4, v227
	v_and_b32_e32 v66, 31, v227
	v_lshrrev_b32_e32 v67, 5, v227
	s_lshl_b32 s50, s7, 4
	v_add_u32_e32 v93, s50, v64
	v_mul_u32_u24_e32 v93, s14, v93
	v_lshl_add_u32 v93, v65, 4, v93
	v_add_u32_e32 v91, s50, v64
	v_mul_u32_u24_e32 v91, s45, v91
	s_and_b32 s50, s0, 3
	s_lshl_b32 s50, s50, 9
	s_lshl_b32 s51, s1, 1
	s_add_i32 s51, s51, s9
	s_lshl_b32 s51, s51, 6
	s_add_i32 s50, s50, s51
	v_lshl_add_u32 v91, v65, 3, v91
	v_add_u32_e32 v91, s50, v91
	s_mul_i32 s50, s9, 8704
	s_add_i32 s50, s50, 91136
	v_mul_u32_u24_e32 v94, s14, v64
	v_lshl_add_u32 v94, v65, 4, v94
	v_add_u32_e32 v94, s50, v94
	s_lshl_b32 s51, s7, 6
	s_add_i32 s51, s51, s50
	v_mul_u32_u24_e32 v95, s14, v66
	v_lshl_add_u32 v95, v67, 3, v95
	v_add_u32_e32 v95, s51, v95
	s_lshl_b32 s50, s7, 7
	s_add_i32 s50, s50, 35840
	v_lshlrev_b32_e32 v88, 4, v67
	v_add_u32_e32 v88, s50, v88
	s_mul_i32 s50, s7, 4608
	s_add_i32 s50, s50, 17408
	v_mul_u32_u24_e32 v89, s15, v66
	v_lshl_add_u32 v89, v67, 4, v89
	v_add_u32_e32 v89, s50, v89
	s_mul_i32 s50, s9, 4608
	s_add_i32 s50, s50, 36352
	v_mul_u32_u24_e32 v90, s15, v66
	v_lshl_add_u32 v90, v67, 4, v90
	v_add_u32_e32 v90, s50, v90
	v_mov_b32_e32 v0, 0
	v_mov_b32_e32 v1, 0
	v_mov_b32_e32 v2, 0
	v_mov_b32_e32 v3, 0
	v_mov_b32_e32 v4, 0
	v_mov_b32_e32 v5, 0
	v_mov_b32_e32 v6, 0
	v_mov_b32_e32 v7, 0
	v_mov_b32_e32 v8, 0
	v_mov_b32_e32 v9, 0
	v_mov_b32_e32 v10, 0
	v_mov_b32_e32 v11, 0
	v_mov_b32_e32 v12, 0
	v_mov_b32_e32 v13, 0
	v_mov_b32_e32 v14, 0
	v_mov_b32_e32 v15, 0
	s_mov_b32 s44, 0
	global_load_dwordx4 v[144:147], v164, s[24:25]
	global_load_dwordx4 v[148:151], v164, s[46:47]
	global_load_dwordx4 v[152:155], v164, s[28:29]
	global_load_dwordx4 v[156:159], v164, s[48:49]
	global_load_dwordx4 v[160:163], v164, s[40:41]
	global_load_dwordx4 v[172:175], v208, s[38:39]
	s_add_u32 s24, s24, 0x4000
	s_addc_u32 s25, s25, 0
	s_add_u32 s46, s46, 0x4000
	s_addc_u32 s47, s47, 0
	s_add_u32 s28, s28, 0x4000
	s_addc_u32 s29, s29, 0
	s_add_u32 s48, s48, 0x4000
	s_addc_u32 s49, s49, 0
	s_add_u32 s40, s40, 0x8000
	s_addc_u32 s41, s41, 0
	s_add_u32 s38, s38, 0x200
	s_addc_u32 s39, s39, 0
	global_load_dwordx4 v[180:183], v164, s[24:25]
	global_load_dwordx4 v[184:187], v164, s[46:47]
	global_load_dwordx4 v[188:191], v164, s[28:29]
	global_load_dwordx4 v[192:195], v164, s[48:49]
	global_load_dwordx4 v[196:199], v164, s[40:41]
	global_load_dwordx4 v[200:203], v208, s[38:39]
	s_add_u32 s24, s24, 0x4000
	s_addc_u32 s25, s25, 0
	s_add_u32 s46, s46, 0x4000
	s_addc_u32 s47, s47, 0
	s_add_u32 s28, s28, 0x4000
	s_addc_u32 s29, s29, 0
	s_add_u32 s48, s48, 0x4000
	s_addc_u32 s49, s49, 0
	s_add_u32 s40, s40, 0x8000
	s_addc_u32 s41, s41, 0
	s_add_u32 s38, s38, 0x200
	s_addc_u32 s39, s39, 0
	global_load_dwordx4 v[204:207], v164, s[24:25]
	global_load_dwordx4 v[212:215], v164, s[46:47]
	global_load_dwordx4 v[216:219], v164, s[28:29]
	global_load_dwordx4 v[236:239], v164, s[48:49]
	global_load_dwordx4 v[80:83], v164, s[40:41]
	global_load_dwordx4 v[84:87], v208, s[38:39]
	s_add_u32 s24, s24, 0x4000
	s_addc_u32 s25, s25, 0
	s_add_u32 s46, s46, 0x4000
	s_addc_u32 s47, s47, 0
	s_add_u32 s28, s28, 0x4000
	s_addc_u32 s29, s29, 0
	s_add_u32 s48, s48, 0x4000
	s_addc_u32 s49, s49, 0
	s_add_u32 s40, s40, 0x8000
	s_addc_u32 s41, s41, 0
	s_add_u32 s38, s38, 0x200
	s_addc_u32 s39, s39, 0
	s_waitcnt vmcnt(12)
	ds_write_b128 v209, v[144:147] offset:0
	ds_write_b128 v209, v[148:151] offset:8704
	ds_write_b128 v210, v[152:155] offset:0
	ds_write_b128 v210, v[156:159] offset:9216
	ds_write_b128 v210, v[160:163] offset:18944
	ds_write_b128 v92, v[172:175] offset:0
	s_waitcnt lgkmcnt(0)
	s_barrier
.Lsc_loop:
.Lsc_body0:
	global_load_dwordx4 v[144:147], v164, s[24:25]
	global_load_dwordx4 v[148:151], v164, s[46:47]
	global_load_dwordx4 v[152:155], v164, s[28:29]
	global_load_dwordx4 v[156:159], v164, s[48:49]
	global_load_dwordx4 v[160:163], v164, s[40:41]
	global_load_dwordx4 v[172:175], v208, s[38:39]
	s_add_u32 s24, s24, 0x4000
	s_addc_u32 s25, s25, 0
	s_add_u32 s46, s46, 0x4000
	s_addc_u32 s47, s47, 0
	s_add_u32 s28, s28, 0x4000
	s_addc_u32 s29, s29, 0
	s_add_u32 s48, s48, 0x4000
	s_addc_u32 s49, s49, 0
	s_add_u32 s40, s40, 0x8000
	s_addc_u32 s41, s41, 0
	s_add_u32 s38, s38, 0x200
	s_addc_u32 s39, s39, 0
	v_cvt_pk_bf16_f32 v16, v0, v1
	v_cvt_pk_bf16_f32 v17, v2, v3
	v_cvt_pk_bf16_f32 v18, v4, v5
	v_cvt_pk_bf16_f32 v19, v6, v7
	v_cvt_pk_bf16_f32 v20, v8, v9
	v_cvt_pk_bf16_f32 v21, v10, v11
	v_cvt_pk_bf16_f32 v22, v12, v13
	v_cvt_pk_bf16_f32 v23, v14, v15
	ds_write_b64 v95, v[16:17] offset:0
	ds_write_b64 v95, v[18:19] offset:16
	ds_write_b64 v95, v[20:21] offset:32
	ds_write_b64 v95, v[22:23] offset:48
	ds_read_b128 v[128:131], v88 offset:0
	ds_read_b128 v[132:135], v88 offset:32
	ds_read_b128 v[136:139], v88 offset:64
	ds_read_b128 v[140:143], v88 offset:96
	ds_read_b128 v[96:99], v89 offset:0
	ds_read_b128 v[100:103], v89 offset:32
	ds_read_b128 v[104:107], v89 offset:64
	ds_read_b128 v[108:111], v89 offset:96
	ds_read_b128 v[112:115], v90 offset:0
	ds_read_b128 v[116:119], v90 offset:32
	ds_read_b128 v[120:123], v90 offset:64
	ds_read_b128 v[124:127], v90 offset:96
	s_waitcnt lgkmcnt(8)
	v_mul_f32_e32 v0, v0, v128
	v_mul_f32_e32 v1, v1, v129
	v_mul_f32_e32 v2, v2, v130
	v_mul_f32_e32 v3, v3, v131
	v_mul_f32_e32 v4, v4, v132
	v_mul_f32_e32 v5, v5, v133
	v_mul_f32_e32 v6, v6, v134
	v_mul_f32_e32 v7, v7, v135
	v_mul_f32_e32 v8, v8, v136
	v_mul_f32_e32 v9, v9, v137
	v_mul_f32_e32 v10, v10, v138
	v_mul_f32_e32 v11, v11, v139
	v_mul_f32_e32 v12, v12, v140
	v_mul_f32_e32 v13, v13, v141
	v_mul_f32_e32 v14, v14, v142
	v_mul_f32_e32 v15, v15, v143
	ds_read_b128 v[64:67], v94 offset:17408
	ds_read_b128 v[68:71], v94 offset:17472
	ds_read_b128 v[72:75], v94 offset:17536
	ds_read_b128 v[76:79], v94 offset:17600
	s_waitcnt lgkmcnt(4)
	v_mfma_f32_32x32x16_bf16 v[0:15], v[96:99], v[112:115], v[0:15]
	v_mfma_f32_32x32x16_bf16 v[0:15], v[100:103], v[116:119], v[0:15]
	v_mfma_f32_32x32x16_bf16 v[0:15], v[104:107], v[120:123], v[0:15]
	v_mfma_f32_32x32x16_bf16 v[0:15], v[108:111], v[124:127], v[0:15]
	ds_read_b128 v[128:131], v94 offset:21760
	ds_read_b128 v[132:135], v94 offset:21824
	ds_read_b128 v[136:139], v94 offset:21888
	ds_read_b128 v[140:143], v94 offset:21952
	ds_read_b128 v[32:35], v93 offset:0
	ds_read_b128 v[36:39], v93 offset:64
	ds_read_b128 v[40:43], v93 offset:128
	ds_read_b128 v[44:47], v93 offset:192
	s_waitcnt lgkmcnt(8)
	v_mfma_f32_16x16x32_bf16 v[24:27], v[64:67], v[48:51], 0
	v_mfma_f32_16x16x32_bf16 v[24:27], v[68:71], v[52:55], v[24:27]
	v_mfma_f32_16x16x32_bf16 v[24:27], v[72:75], v[56:59], v[24:27]
	v_mfma_f32_16x16x32_bf16 v[24:27], v[76:79], v[60:63], v[24:27]
	s_waitcnt lgkmcnt(4)
	v_mfma_f32_16x16x32_bf16 v[28:31], v[128:131], v[48:51], 0
	v_mfma_f32_16x16x32_bf16 v[28:31], v[132:135], v[52:55], v[28:31]
	v_mfma_f32_16x16x32_bf16 v[28:31], v[136:139], v[56:59], v[28:31]
	v_mfma_f32_16x16x32_bf16 v[28:31], v[140:143], v[60:63], v[28:31]
	s_waitcnt vmcnt(12)
	ds_write_b128 v209, v[180:183] offset:45568
	ds_write_b128 v209, v[184:187] offset:54272
	ds_write_b128 v210, v[188:191] offset:45568
	ds_write_b128 v210, v[192:195] offset:54784
	ds_write_b128 v210, v[196:199] offset:64512
	ds_write_b128 v92, v[200:203] offset:45568
	s_cmp_eq_u32 s44, 0
	s_cbranch_scc1 .Lsc_nost_k0
	v_cvt_pk_bf16_f32 v24, v24, v25
	v_cvt_pk_bf16_f32 v25, v26, v27
	v_cvt_pk_bf16_f32 v28, v28, v29
	v_cvt_pk_bf16_f32 v29, v30, v31
	global_store_dwordx2 v91, v[24:25], s[42:43]
	global_store_dwordx2 v91, v[28:29], s[42:43] offset:32
	s_add_u32 s42, s42, 0x68000
	s_addc_u32 s43, s43, 0
.Lsc_nost_k0:
	s_add_i32 s44, s44, 1
	s_waitcnt lgkmcnt(0)
	s_barrier
.Lsc_body1:
	s_cmp_lt_u32 s44, 61
	s_cbranch_scc0 .Lsc_nold_k1
	global_load_dwordx4 v[180:183], v164, s[24:25]
	global_load_dwordx4 v[184:187], v164, s[46:47]
	global_load_dwordx4 v[188:191], v164, s[28:29]
	global_load_dwordx4 v[192:195], v164, s[48:49]
	global_load_dwordx4 v[196:199], v164, s[40:41]
	global_load_dwordx4 v[200:203], v208, s[38:39]
	s_add_u32 s24, s24, 0x4000
	s_addc_u32 s25, s25, 0
	s_add_u32 s46, s46, 0x4000
	s_addc_u32 s47, s47, 0
	s_add_u32 s28, s28, 0x4000
	s_addc_u32 s29, s29, 0
	s_add_u32 s48, s48, 0x4000
	s_addc_u32 s49, s49, 0
	s_add_u32 s40, s40, 0x8000
	s_addc_u32 s41, s41, 0
	s_add_u32 s38, s38, 0x200
	s_addc_u32 s39, s39, 0
.Lsc_nold_k1:
	v_cvt_pk_bf16_f32 v16, v0, v1
	v_cvt_pk_bf16_f32 v17, v2, v3
	v_cvt_pk_bf16_f32 v18, v4, v5
	v_cvt_pk_bf16_f32 v19, v6, v7
	v_cvt_pk_bf16_f32 v20, v8, v9
	v_cvt_pk_bf16_f32 v21, v10, v11
	v_cvt_pk_bf16_f32 v22, v12, v13
	v_cvt_pk_bf16_f32 v23, v14, v15
	ds_write_b64 v95, v[16:17] offset:17408
	ds_write_b64 v95, v[18:19] offset:17424
	ds_write_b64 v95, v[20:21] offset:17440
	ds_write_b64 v95, v[22:23] offset:17456
	ds_read_b128 v[128:131], v88 offset:45568
	ds_read_b128 v[132:135], v88 offset:45600
	ds_read_b128 v[136:139], v88 offset:45632
	ds_read_b128 v[140:143], v88 offset:45664
	ds_read_b128 v[96:99], v89 offset:45568
	ds_read_b128 v[100:103], v89 offset:45600
	ds_read_b128 v[104:107], v89 offset:45632
	ds_read_b128 v[108:111], v89 offset:45664
	ds_read_b128 v[112:115], v90 offset:45568
	ds_read_b128 v[116:119], v90 offset:45600
	ds_read_b128 v[120:123], v90 offset:45632
	ds_read_b128 v[124:127], v90 offset:45664
	s_waitcnt lgkmcnt(8)
	v_mul_f32_e32 v0, v0, v128
	v_mul_f32_e32 v1, v1, v129
	v_mul_f32_e32 v2, v2, v130
	v_mul_f32_e32 v3, v3, v131
	v_mul_f32_e32 v4, v4, v132
	v_mul_f32_e32 v5, v5, v133
	v_mul_f32_e32 v6, v6, v134
	v_mul_f32_e32 v7, v7, v135
	v_mul_f32_e32 v8, v8, v136
	v_mul_f32_e32 v9, v9, v137
	v_mul_f32_e32 v10, v10, v138
	v_mul_f32_e32 v11, v11, v139
	v_mul_f32_e32 v12, v12, v140
	v_mul_f32_e32 v13, v13, v141
	v_mul_f32_e32 v14, v14, v142
	v_mul_f32_e32 v15, v15, v143
	ds_read_b128 v[64:67], v94 offset:0
	ds_read_b128 v[68:71], v94 offset:64
	ds_read_b128 v[72:75], v94 offset:128
	ds_read_b128 v[76:79], v94 offset:192
	s_waitcnt lgkmcnt(4)
	v_mfma_f32_32x32x16_bf16 v[0:15], v[96:99], v[112:115], v[0:15]
	v_mfma_f32_32x32x16_bf16 v[0:15], v[100:103], v[116:119], v[0:15]
	v_mfma_f32_32x32x16_bf16 v[0:15], v[104:107], v[120:123], v[0:15]
	v_mfma_f32_32x32x16_bf16 v[0:15], v[108:111], v[124:127], v[0:15]
	ds_read_b128 v[128:131], v94 offset:4352
	ds_read_b128 v[132:135], v94 offset:4416
	ds_read_b128 v[136:139], v94 offset:4480
	ds_read_b128 v[140:143], v94 offset:4544
	ds_read_b128 v[48:51], v93 offset:45568
	ds_read_b128 v[52:55], v93 offset:45632
	ds_read_b128 v[56:59], v93 offset:45696
	ds_read_b128 v[60:63], v93 offset:45760
	s_waitcnt lgkmcnt(8)
	v_mfma_f32_16x16x32_bf16 v[24:27], v[64:67], v[32:35], 0
	v_mfma_f32_16x16x32_bf16 v[24:27], v[68:71], v[36:39], v[24:27]
	v_mfma_f32_16x16x32_bf16 v[24:27], v[72:75], v[40:43], v[24:27]
	v_mfma_f32_16x16x32_bf16 v[24:27], v[76:79], v[44:47], v[24:27]
	s_waitcnt lgkmcnt(4)
	v_mfma_f32_16x16x32_bf16 v[28:31], v[128:131], v[32:35], 0
	v_mfma_f32_16x16x32_bf16 v[28:31], v[132:135], v[36:39], v[28:31]
	v_mfma_f32_16x16x32_bf16 v[28:31], v[136:139], v[40:43], v[28:31]
	v_mfma_f32_16x16x32_bf16 v[28:31], v[140:143], v[44:47], v[28:31]
	s_cmp_lt_u32 s44, 61
	s_cbranch_scc1 .Lsc_w12_k1
	s_waitcnt vmcnt(0)
	s_branch .Lsc_wd_k1

.Lsc_wd_k1:
	ds_write_b128 v209, v[204:207] offset:0
	ds_write_b128 v209, v[212:215] offset:8704
	ds_write_b128 v210, v[216:219] offset:0
	ds_write_b128 v210, v[236:239] offset:9216
	ds_write_b128 v210, v[80:83] offset:18944
	ds_write_b128 v92, v[84:87] offset:0
	v_cvt_pk_bf16_f32 v24, v24, v25
	v_cvt_pk_bf16_f32 v25, v26, v27
	v_cvt_pk_bf16_f32 v28, v28, v29
	v_cvt_pk_bf16_f32 v29, v30, v31
	global_store_dwordx2 v91, v[24:25], s[42:43]
	global_store_dwordx2 v91, v[28:29], s[42:43] offset:32
	s_add_u32 s42, s42, 0x68000
	s_addc_u32 s43, s43, 0
	s_add_i32 s44, s44, 1
	s_waitcnt lgkmcnt(0)
	s_barrier
.Lsc_body2:
	s_cmp_lt_u32 s44, 61
	s_cbranch_scc0 .Lsc_nold_k2
	global_load_dwordx4 v[204:207], v164, s[24:25]
	global_load_dwordx4 v[212:215], v164, s[46:47]
	global_load_dwordx4 v[216:219], v164, s[28:29]
	global_load_dwordx4 v[236:239], v164, s[48:49]
	global_load_dwordx4 v[80:83], v164, s[40:41]
	global_load_dwordx4 v[84:87], v208, s[38:39]
	s_add_u32 s24, s24, 0x4000
	s_addc_u32 s25, s25, 0
	s_add_u32 s46, s46, 0x4000
	s_addc_u32 s47, s47, 0
	s_add_u32 s28, s28, 0x4000
	s_addc_u32 s29, s29, 0
	s_add_u32 s48, s48, 0x4000
	s_addc_u32 s49, s49, 0
	s_add_u32 s40, s40, 0x8000
	s_addc_u32 s41, s41, 0
	s_add_u32 s38, s38, 0x200
	s_addc_u32 s39, s39, 0
.Lsc_nold_k2:
	v_cvt_pk_bf16_f32 v16, v0, v1
	v_cvt_pk_bf16_f32 v17, v2, v3
	v_cvt_pk_bf16_f32 v18, v4, v5
	v_cvt_pk_bf16_f32 v19, v6, v7
	v_cvt_pk_bf16_f32 v20, v8, v9
	v_cvt_pk_bf16_f32 v21, v10, v11
	v_cvt_pk_bf16_f32 v22, v12, v13
	v_cvt_pk_bf16_f32 v23, v14, v15
	ds_write_b64 v95, v[16:17] offset:0
	ds_write_b64 v95, v[18:19] offset:16
	ds_write_b64 v95, v[20:21] offset:32
	ds_write_b64 v95, v[22:23] offset:48
	ds_read_b128 v[128:131], v88 offset:0
	ds_read_b128 v[132:135], v88 offset:32
	ds_read_b128 v[136:139], v88 offset:64
	ds_read_b128 v[140:143], v88 offset:96
	ds_read_b128 v[96:99], v89 offset:0
	ds_read_b128 v[100:103], v89 offset:32
	ds_read_b128 v[104:107], v89 offset:64
	ds_read_b128 v[108:111], v89 offset:96
	ds_read_b128 v[112:115], v90 offset:0
	ds_read_b128 v[116:119], v90 offset:32
	ds_read_b128 v[120:123], v90 offset:64
	ds_read_b128 v[124:127], v90 offset:96
	s_waitcnt lgkmcnt(8)
	v_mul_f32_e32 v0, v0, v128
	v_mul_f32_e32 v1, v1, v129
	v_mul_f32_e32 v2, v2, v130
	v_mul_f32_e32 v3, v3, v131
	v_mul_f32_e32 v4, v4, v132
	v_mul_f32_e32 v5, v5, v133
	v_mul_f32_e32 v6, v6, v134
	v_mul_f32_e32 v7, v7, v135
	v_mul_f32_e32 v8, v8, v136
	v_mul_f32_e32 v9, v9, v137
	v_mul_f32_e32 v10, v10, v138
	v_mul_f32_e32 v11, v11, v139
	v_mul_f32_e32 v12, v12, v140
	v_mul_f32_e32 v13, v13, v141
	v_mul_f32_e32 v14, v14, v142
	v_mul_f32_e32 v15, v15, v143
	ds_read_b128 v[64:67], v94 offset:17408
	ds_read_b128 v[68:71], v94 offset:17472
	ds_read_b128 v[72:75], v94 offset:17536
	ds_read_b128 v[76:79], v94 offset:17600
	s_waitcnt lgkmcnt(4)
	v_mfma_f32_32x32x16_bf16 v[0:15], v[96:99], v[112:115], v[0:15]
	v_mfma_f32_32x32x16_bf16 v[0:15], v[100:103], v[116:119], v[0:15]
	v_mfma_f32_32x32x16_bf16 v[0:15], v[104:107], v[120:123], v[0:15]
	v_mfma_f32_32x32x16_bf16 v[0:15], v[108:111], v[124:127], v[0:15]
	ds_read_b128 v[128:131], v94 offset:21760
	ds_read_b128 v[132:135], v94 offset:21824
	ds_read_b128 v[136:139], v94 offset:21888
	ds_read_b128 v[140:143], v94 offset:21952
	ds_read_b128 v[32:35], v93 offset:0
	ds_read_b128 v[36:39], v93 offset:64
	ds_read_b128 v[40:43], v93 offset:128
	ds_read_b128 v[44:47], v93 offset:192
	s_waitcnt lgkmcnt(8)
	v_mfma_f32_16x16x32_bf16 v[24:27], v[64:67], v[48:51], 0
	v_mfma_f32_16x16x32_bf16 v[24:27], v[68:71], v[52:55], v[24:27]
	v_mfma_f32_16x16x32_bf16 v[24:27], v[72:75], v[56:59], v[24:27]
	v_mfma_f32_16x16x32_bf16 v[24:27], v[76:79], v[60:63], v[24:27]
	s_waitcnt lgkmcnt(4)
	v_mfma_f32_16x16x32_bf16 v[28:31], v[128:131], v[48:51], 0
	v_mfma_f32_16x16x32_bf16 v[28:31], v[132:135], v[52:55], v[28:31]
	v_mfma_f32_16x16x32_bf16 v[28:31], v[136:139], v[56:59], v[28:31]
	v_mfma_f32_16x16x32_bf16 v[28:31], v[140:143], v[60:63], v[28:31]
	s_cmp_lt_u32 s44, 61
	s_cbranch_scc1 .Lsc_w12_k2
	s_waitcnt vmcnt(0)
	s_branch .Lsc_wd_k2

.Lsc_wd_k2:
	ds_write_b128 v209, v[144:147] offset:45568
	ds_write_b128 v209, v[148:151] offset:54272
	ds_write_b128 v210, v[152:155] offset:45568
	ds_write_b128 v210, v[156:159] offset:54784
	ds_write_b128 v210, v[160:163] offset:64512
	ds_write_b128 v92, v[172:175] offset:45568
	v_cvt_pk_bf16_f32 v24, v24, v25
	v_cvt_pk_bf16_f32 v25, v26, v27
	v_cvt_pk_bf16_f32 v28, v28, v29
	v_cvt_pk_bf16_f32 v29, v30, v31
	global_store_dwordx2 v91, v[24:25], s[42:43]
	global_store_dwordx2 v91, v[28:29], s[42:43] offset:32
	s_add_u32 s42, s42, 0x68000
	s_addc_u32 s43, s43, 0
	s_add_i32 s44, s44, 1
	s_waitcnt lgkmcnt(0)
	s_barrier
.Lsc_body3:
	s_cmp_lt_u32 s44, 61
	s_cbranch_scc0 .Lsc_nold_k3
	global_load_dwordx4 v[144:147], v164, s[24:25]
	global_load_dwordx4 v[148:151], v164, s[46:47]
	global_load_dwordx4 v[152:155], v164, s[28:29]
	global_load_dwordx4 v[156:159], v164, s[48:49]
	global_load_dwordx4 v[160:163], v164, s[40:41]
	global_load_dwordx4 v[172:175], v208, s[38:39]
	s_add_u32 s24, s24, 0x4000
	s_addc_u32 s25, s25, 0
	s_add_u32 s46, s46, 0x4000
	s_addc_u32 s47, s47, 0
	s_add_u32 s28, s28, 0x4000
	s_addc_u32 s29, s29, 0
	s_add_u32 s48, s48, 0x4000
	s_addc_u32 s49, s49, 0
	s_add_u32 s40, s40, 0x8000
	s_addc_u32 s41, s41, 0
	s_add_u32 s38, s38, 0x200
	s_addc_u32 s39, s39, 0
.Lsc_nold_k3:
	v_cvt_pk_bf16_f32 v16, v0, v1
	v_cvt_pk_bf16_f32 v17, v2, v3
	v_cvt_pk_bf16_f32 v18, v4, v5
	v_cvt_pk_bf16_f32 v19, v6, v7
	v_cvt_pk_bf16_f32 v20, v8, v9
	v_cvt_pk_bf16_f32 v21, v10, v11
	v_cvt_pk_bf16_f32 v22, v12, v13
	v_cvt_pk_bf16_f32 v23, v14, v15
	ds_write_b64 v95, v[16:17] offset:17408
	ds_write_b64 v95, v[18:19] offset:17424
	ds_write_b64 v95, v[20:21] offset:17440
	ds_write_b64 v95, v[22:23] offset:17456
	ds_read_b128 v[128:131], v88 offset:45568
	ds_read_b128 v[132:135], v88 offset:45600
	ds_read_b128 v[136:139], v88 offset:45632
	ds_read_b128 v[140:143], v88 offset:45664
	ds_read_b128 v[96:99], v89 offset:45568
	ds_read_b128 v[100:103], v89 offset:45600
	ds_read_b128 v[104:107], v89 offset:45632
	ds_read_b128 v[108:111], v89 offset:45664
	ds_read_b128 v[112:115], v90 offset:45568
	ds_read_b128 v[116:119], v90 offset:45600
	ds_read_b128 v[120:123], v90 offset:45632
	ds_read_b128 v[124:127], v90 offset:45664
	s_waitcnt lgkmcnt(8)
	v_mul_f32_e32 v0, v0, v128
	v_mul_f32_e32 v1, v1, v129
	v_mul_f32_e32 v2, v2, v130
	v_mul_f32_e32 v3, v3, v131
	v_mul_f32_e32 v4, v4, v132
	v_mul_f32_e32 v5, v5, v133
	v_mul_f32_e32 v6, v6, v134
	v_mul_f32_e32 v7, v7, v135
	v_mul_f32_e32 v8, v8, v136
	v_mul_f32_e32 v9, v9, v137
	v_mul_f32_e32 v10, v10, v138
	v_mul_f32_e32 v11, v11, v139
	v_mul_f32_e32 v12, v12, v140
	v_mul_f32_e32 v13, v13, v141
	v_mul_f32_e32 v14, v14, v142
	v_mul_f32_e32 v15, v15, v143
	ds_read_b128 v[64:67], v94 offset:0
	ds_read_b128 v[68:71], v94 offset:64
	ds_read_b128 v[72:75], v94 offset:128
	ds_read_b128 v[76:79], v94 offset:192
	s_waitcnt lgkmcnt(4)
	v_mfma_f32_32x32x16_bf16 v[0:15], v[96:99], v[112:115], v[0:15]
	v_mfma_f32_32x32x16_bf16 v[0:15], v[100:103], v[116:119], v[0:15]
	v_mfma_f32_32x32x16_bf16 v[0:15], v[104:107], v[120:123], v[0:15]
	v_mfma_f32_32x32x16_bf16 v[0:15], v[108:111], v[124:127], v[0:15]
	ds_read_b128 v[128:131], v94 offset:4352
	ds_read_b128 v[132:135], v94 offset:4416
	ds_read_b128 v[136:139], v94 offset:4480
	ds_read_b128 v[140:143], v94 offset:4544
	ds_read_b128 v[48:51], v93 offset:45568
	ds_read_b128 v[52:55], v93 offset:45632
	ds_read_b128 v[56:59], v93 offset:45696
	ds_read_b128 v[60:63], v93 offset:45760
	s_waitcnt lgkmcnt(8)
	v_mfma_f32_16x16x32_bf16 v[24:27], v[64:67], v[32:35], 0
	v_mfma_f32_16x16x32_bf16 v[24:27], v[68:71], v[36:39], v[24:27]
	v_mfma_f32_16x16x32_bf16 v[24:27], v[72:75], v[40:43], v[24:27]
	v_mfma_f32_16x16x32_bf16 v[24:27], v[76:79], v[44:47], v[24:27]
	s_waitcnt lgkmcnt(4)
	v_mfma_f32_16x16x32_bf16 v[28:31], v[128:131], v[32:35], 0
	v_mfma_f32_16x16x32_bf16 v[28:31], v[132:135], v[36:39], v[28:31]
	v_mfma_f32_16x16x32_bf16 v[28:31], v[136:139], v[40:43], v[28:31]
	v_mfma_f32_16x16x32_bf16 v[28:31], v[140:143], v[44:47], v[28:31]
	s_nop 7
	s_cmp_lt_u32 s44, 63
	s_cbranch_scc0 .Lsc_nostage_k3
	s_cmp_lt_u32 s44, 61
	s_cbranch_scc1 .Lsc_w12_k3
	s_waitcnt vmcnt(0)
	s_branch .Lsc_wd_k3

.Lsc_wd_k3:
	ds_write_b128 v209, v[180:183] offset:0
	ds_write_b128 v209, v[184:187] offset:8704
	ds_write_b128 v210, v[188:191] offset:0
	ds_write_b128 v210, v[192:195] offset:9216
	ds_write_b128 v210, v[196:199] offset:18944
	ds_write_b128 v92, v[200:203] offset:0
.Lsc_nostage_k3:
	v_cvt_pk_bf16_f32 v24, v24, v25
	v_cvt_pk_bf16_f32 v25, v26, v27
	v_cvt_pk_bf16_f32 v28, v28, v29
	v_cvt_pk_bf16_f32 v29, v30, v31
	global_store_dwordx2 v91, v[24:25], s[42:43]
	global_store_dwordx2 v91, v[28:29], s[42:43] offset:32
	s_add_u32 s42, s42, 0x68000
	s_addc_u32 s43, s43, 0
	s_add_i32 s44, s44, 1
	s_waitcnt lgkmcnt(0)
	s_barrier
	s_cmp_eq_u32 s44, 64
	s_cbranch_scc1 .Lsc_epi
.Lsc_body4:
	global_load_dwordx4 v[180:183], v164, s[24:25]
	global_load_dwordx4 v[184:187], v164, s[46:47]
	global_load_dwordx4 v[188:191], v164, s[28:29]
	global_load_dwordx4 v[192:195], v164, s[48:49]
	global_load_dwordx4 v[196:199], v164, s[40:41]
	global_load_dwordx4 v[200:203], v208, s[38:39]
	s_add_u32 s24, s24, 0x4000
	s_addc_u32 s25, s25, 0
	s_add_u32 s46, s46, 0x4000
	s_addc_u32 s47, s47, 0
	s_add_u32 s28, s28, 0x4000
	s_addc_u32 s29, s29, 0
	s_add_u32 s48, s48, 0x4000
	s_addc_u32 s49, s49, 0
	s_add_u32 s40, s40, 0x8000
	s_addc_u32 s41, s41, 0
	s_add_u32 s38, s38, 0x200
	s_addc_u32 s39, s39, 0
	v_cvt_pk_bf16_f32 v16, v0, v1
	v_cvt_pk_bf16_f32 v17, v2, v3
	v_cvt_pk_bf16_f32 v18, v4, v5
	v_cvt_pk_bf16_f32 v19, v6, v7
	v_cvt_pk_bf16_f32 v20, v8, v9
	v_cvt_pk_bf16_f32 v21, v10, v11
	v_cvt_pk_bf16_f32 v22, v12, v13
	v_cvt_pk_bf16_f32 v23, v14, v15
	ds_write_b64 v95, v[16:17] offset:0
	ds_write_b64 v95, v[18:19] offset:16
	ds_write_b64 v95, v[20:21] offset:32
	ds_write_b64 v95, v[22:23] offset:48
	ds_read_b128 v[128:131], v88 offset:0
	ds_read_b128 v[132:135], v88 offset:32
	ds_read_b128 v[136:139], v88 offset:64
	ds_read_b128 v[140:143], v88 offset:96
	ds_read_b128 v[96:99], v89 offset:0
	ds_read_b128 v[100:103], v89 offset:32
	ds_read_b128 v[104:107], v89 offset:64
	ds_read_b128 v[108:111], v89 offset:96
	ds_read_b128 v[112:115], v90 offset:0
	ds_read_b128 v[116:119], v90 offset:32
	ds_read_b128 v[120:123], v90 offset:64
	ds_read_b128 v[124:127], v90 offset:96
	s_waitcnt lgkmcnt(8)
	v_mul_f32_e32 v0, v0, v128
	v_mul_f32_e32 v1, v1, v129
	v_mul_f32_e32 v2, v2, v130
	v_mul_f32_e32 v3, v3, v131
	v_mul_f32_e32 v4, v4, v132
	v_mul_f32_e32 v5, v5, v133
	v_mul_f32_e32 v6, v6, v134
	v_mul_f32_e32 v7, v7, v135
	v_mul_f32_e32 v8, v8, v136
	v_mul_f32_e32 v9, v9, v137
	v_mul_f32_e32 v10, v10, v138
	v_mul_f32_e32 v11, v11, v139
	v_mul_f32_e32 v12, v12, v140
	v_mul_f32_e32 v13, v13, v141
	v_mul_f32_e32 v14, v14, v142
	v_mul_f32_e32 v15, v15, v143
	ds_read_b128 v[64:67], v94 offset:17408
	ds_read_b128 v[68:71], v94 offset:17472
	ds_read_b128 v[72:75], v94 offset:17536
	ds_read_b128 v[76:79], v94 offset:17600
	s_waitcnt lgkmcnt(4)
	v_mfma_f32_32x32x16_bf16 v[0:15], v[96:99], v[112:115], v[0:15]
	v_mfma_f32_32x32x16_bf16 v[0:15], v[100:103], v[116:119], v[0:15]
	v_mfma_f32_32x32x16_bf16 v[0:15], v[104:107], v[120:123], v[0:15]
	v_mfma_f32_32x32x16_bf16 v[0:15], v[108:111], v[124:127], v[0:15]
	ds_read_b128 v[128:131], v94 offset:21760
	ds_read_b128 v[132:135], v94 offset:21824
	ds_read_b128 v[136:139], v94 offset:21888
	ds_read_b128 v[140:143], v94 offset:21952
	ds_read_b128 v[32:35], v93 offset:0
	ds_read_b128 v[36:39], v93 offset:64
	ds_read_b128 v[40:43], v93 offset:128
	ds_read_b128 v[44:47], v93 offset:192
	s_waitcnt lgkmcnt(8)
	v_mfma_f32_16x16x32_bf16 v[24:27], v[64:67], v[48:51], 0
	v_mfma_f32_16x16x32_bf16 v[24:27], v[68:71], v[52:55], v[24:27]
	v_mfma_f32_16x16x32_bf16 v[24:27], v[72:75], v[56:59], v[24:27]
	v_mfma_f32_16x16x32_bf16 v[24:27], v[76:79], v[60:63], v[24:27]
	s_waitcnt lgkmcnt(4)
	v_mfma_f32_16x16x32_bf16 v[28:31], v[128:131], v[48:51], 0
	v_mfma_f32_16x16x32_bf16 v[28:31], v[132:135], v[52:55], v[28:31]
	v_mfma_f32_16x16x32_bf16 v[28:31], v[136:139], v[56:59], v[28:31]
	v_mfma_f32_16x16x32_bf16 v[28:31], v[140:143], v[60:63], v[28:31]
	s_waitcnt vmcnt(12)
	ds_write_b128 v209, v[204:207] offset:45568
	ds_write_b128 v209, v[212:215] offset:54272
	ds_write_b128 v210, v[216:219] offset:45568
	ds_write_b128 v210, v[236:239] offset:54784
	ds_write_b128 v210, v[80:83] offset:64512
	ds_write_b128 v92, v[84:87] offset:45568
	v_cvt_pk_bf16_f32 v24, v24, v25
	v_cvt_pk_bf16_f32 v25, v26, v27
	v_cvt_pk_bf16_f32 v28, v28, v29
	v_cvt_pk_bf16_f32 v29, v30, v31
	global_store_dwordx2 v91, v[24:25], s[42:43]
	global_store_dwordx2 v91, v[28:29], s[42:43] offset:32
	s_add_u32 s42, s42, 0x68000
	s_addc_u32 s43, s43, 0
	s_add_i32 s44, s44, 1
	s_waitcnt lgkmcnt(0)
	s_barrier
.Lsc_body5:
	global_load_dwordx4 v[204:207], v164, s[24:25]
	global_load_dwordx4 v[212:215], v164, s[46:47]
	global_load_dwordx4 v[216:219], v164, s[28:29]
	global_load_dwordx4 v[236:239], v164, s[48:49]
	global_load_dwordx4 v[80:83], v164, s[40:41]
	global_load_dwordx4 v[84:87], v208, s[38:39]
	s_add_u32 s24, s24, 0x4000
	s_addc_u32 s25, s25, 0
	s_add_u32 s46, s46, 0x4000
	s_addc_u32 s47, s47, 0
	s_add_u32 s28, s28, 0x4000
	s_addc_u32 s29, s29, 0
	s_add_u32 s48, s48, 0x4000
	s_addc_u32 s49, s49, 0
	s_add_u32 s40, s40, 0x8000
	s_addc_u32 s41, s41, 0
	s_add_u32 s38, s38, 0x200
	s_addc_u32 s39, s39, 0
	v_cvt_pk_bf16_f32 v16, v0, v1
	v_cvt_pk_bf16_f32 v17, v2, v3
	v_cvt_pk_bf16_f32 v18, v4, v5
	v_cvt_pk_bf16_f32 v19, v6, v7
	v_cvt_pk_bf16_f32 v20, v8, v9
	v_cvt_pk_bf16_f32 v21, v10, v11
	v_cvt_pk_bf16_f32 v22, v12, v13
	v_cvt_pk_bf16_f32 v23, v14, v15
	ds_write_b64 v95, v[16:17] offset:17408
	ds_write_b64 v95, v[18:19] offset:17424
	ds_write_b64 v95, v[20:21] offset:17440
	ds_write_b64 v95, v[22:23] offset:17456
	ds_read_b128 v[128:131], v88 offset:45568
	ds_read_b128 v[132:135], v88 offset:45600
	ds_read_b128 v[136:139], v88 offset:45632
	ds_read_b128 v[140:143], v88 offset:45664
	ds_read_b128 v[96:99], v89 offset:45568
	ds_read_b128 v[100:103], v89 offset:45600
	ds_read_b128 v[104:107], v89 offset:45632
	ds_read_b128 v[108:111], v89 offset:45664
	ds_read_b128 v[112:115], v90 offset:45568
	ds_read_b128 v[116:119], v90 offset:45600
	ds_read_b128 v[120:123], v90 offset:45632
	ds_read_b128 v[124:127], v90 offset:45664
	s_waitcnt lgkmcnt(8)
	v_mul_f32_e32 v0, v0, v128
	v_mul_f32_e32 v1, v1, v129
	v_mul_f32_e32 v2, v2, v130
	v_mul_f32_e32 v3, v3, v131
	v_mul_f32_e32 v4, v4, v132
	v_mul_f32_e32 v5, v5, v133
	v_mul_f32_e32 v6, v6, v134
	v_mul_f32_e32 v7, v7, v135
	v_mul_f32_e32 v8, v8, v136
	v_mul_f32_e32 v9, v9, v137
	v_mul_f32_e32 v10, v10, v138
	v_mul_f32_e32 v11, v11, v139
	v_mul_f32_e32 v12, v12, v140
	v_mul_f32_e32 v13, v13, v141
	v_mul_f32_e32 v14, v14, v142
	v_mul_f32_e32 v15, v15, v143
	ds_read_b128 v[64:67], v94 offset:0
	ds_read_b128 v[68:71], v94 offset:64
	ds_read_b128 v[72:75], v94 offset:128
	ds_read_b128 v[76:79], v94 offset:192
	s_waitcnt lgkmcnt(4)
	v_mfma_f32_32x32x16_bf16 v[0:15], v[96:99], v[112:115], v[0:15]
	v_mfma_f32_32x32x16_bf16 v[0:15], v[100:103], v[116:119], v[0:15]
	v_mfma_f32_32x32x16_bf16 v[0:15], v[104:107], v[120:123], v[0:15]
	v_mfma_f32_32x32x16_bf16 v[0:15], v[108:111], v[124:127], v[0:15]
	ds_read_b128 v[128:131], v94 offset:4352
	ds_read_b128 v[132:135], v94 offset:4416
	ds_read_b128 v[136:139], v94 offset:4480
	ds_read_b128 v[140:143], v94 offset:4544
	ds_read_b128 v[48:51], v93 offset:45568
	ds_read_b128 v[52:55], v93 offset:45632
	ds_read_b128 v[56:59], v93 offset:45696
	ds_read_b128 v[60:63], v93 offset:45760
	s_waitcnt lgkmcnt(8)
	v_mfma_f32_16x16x32_bf16 v[24:27], v[64:67], v[32:35], 0
	v_mfma_f32_16x16x32_bf16 v[24:27], v[68:71], v[36:39], v[24:27]
	v_mfma_f32_16x16x32_bf16 v[24:27], v[72:75], v[40:43], v[24:27]
	v_mfma_f32_16x16x32_bf16 v[24:27], v[76:79], v[44:47], v[24:27]
	s_waitcnt lgkmcnt(4)
	v_mfma_f32_16x16x32_bf16 v[28:31], v[128:131], v[32:35], 0
	v_mfma_f32_16x16x32_bf16 v[28:31], v[132:135], v[36:39], v[28:31]
	v_mfma_f32_16x16x32_bf16 v[28:31], v[136:139], v[40:43], v[28:31]
	v_mfma_f32_16x16x32_bf16 v[28:31], v[140:143], v[44:47], v[28:31]
	s_waitcnt vmcnt(12)
	ds_write_b128 v209, v[144:147] offset:0
	ds_write_b128 v209, v[148:151] offset:8704
	ds_write_b128 v210, v[152:155] offset:0
	ds_write_b128 v210, v[156:159] offset:9216
	ds_write_b128 v210, v[160:163] offset:18944
	ds_write_b128 v92, v[172:175] offset:0
	v_cvt_pk_bf16_f32 v24, v24, v25
	v_cvt_pk_bf16_f32 v25, v26, v27
	v_cvt_pk_bf16_f32 v28, v28, v29
	v_cvt_pk_bf16_f32 v29, v30, v31
	global_store_dwordx2 v91, v[24:25], s[42:43]
	global_store_dwordx2 v91, v[28:29], s[42:43] offset:32
	s_add_u32 s42, s42, 0x68000
	s_addc_u32 s43, s43, 0
	s_add_i32 s44, s44, 1
	s_waitcnt lgkmcnt(0)
	s_barrier
	s_branch .Lsc_loop
.Lsc_epi:
	ds_read_b128 v[64:67], v94 offset:17408
	ds_read_b128 v[68:71], v94 offset:17472
	ds_read_b128 v[72:75], v94 offset:17536
	ds_read_b128 v[76:79], v94 offset:17600
	ds_read_b128 v[128:131], v94 offset:21760
	ds_read_b128 v[132:135], v94 offset:21824
	ds_read_b128 v[136:139], v94 offset:21888
	ds_read_b128 v[140:143], v94 offset:21952
	s_waitcnt lgkmcnt(4)
	v_mfma_f32_16x16x32_bf16 v[24:27], v[64:67], v[48:51], 0
	v_mfma_f32_16x16x32_bf16 v[24:27], v[68:71], v[52:55], v[24:27]
	v_mfma_f32_16x16x32_bf16 v[24:27], v[72:75], v[56:59], v[24:27]
	v_mfma_f32_16x16x32_bf16 v[24:27], v[76:79], v[60:63], v[24:27]
	s_waitcnt lgkmcnt(0)
	v_mfma_f32_16x16x32_bf16 v[28:31], v[128:131], v[48:51], 0
	v_mfma_f32_16x16x32_bf16 v[28:31], v[132:135], v[52:55], v[28:31]
	v_mfma_f32_16x16x32_bf16 v[28:31], v[136:139], v[56:59], v[28:31]
	v_mfma_f32_16x16x32_bf16 v[28:31], v[140:143], v[60:63], v[28:31]
	s_nop 7
	s_nop 3
	v_cvt_pk_bf16_f32 v24, v24, v25
	v_cvt_pk_bf16_f32 v25, v26, v27
	v_cvt_pk_bf16_f32 v28, v28, v29
	v_cvt_pk_bf16_f32 v29, v30, v31
	global_store_dwordx2 v91, v[24:25], s[42:43]
	global_store_dwordx2 v91, v[28:29], s[42:43] offset:32
	s_add_u32 s42, s42, 0x68000
	s_addc_u32 s43, s43, 0
	s_branch .LBB0_176
